# v61 + k-block mean loads all 64 in flight; decay prefix scan moved next to the early gate math on wave 6
# speedup vs baseline: 1.0041x; 1.0041x over previous
; __device__ __forceinline__ void lds_barrier() { asm volatile("s_waitcnt lgkmcnt(0)" ::: "memory"); __builtin_amdgcn_s_barrier(); asm volatile("" ::: "memory"); }
; __device__ __forceinline__ void gdn_local_unit(LAS unsigned char* lds, const GdnP& P, int unit, const int tid, const int pf) {
;     ...
;         beta[t] = 1.f / (1.f + expf(-bl)); const float x = al + P.dt_bias[h]; const float sp = x > 20.f ? x : log1pf(expf(x)); gb[t] = -expf(P.a_log[h]) * sp; }
;     lds_barrier();
;     if (tid < 64) { float v = gb[tid];
; #pragma unroll
;         for (int o = 1; o < 64; o <<= 1) { const float y = __shfl_up(v, o); if (lane >= o) v += y; }
;         Gc[tid] = v; eG[tid] = expf(v); }
.Lge_892:
	s_or_b64 exec, exec, s[42:43]
	v_mov_b32_e32 v2, v245
	v_mul_f32_e32 v3, 0x3fb8aa3b, v2
	v_fma_f32 v4, v2, s88, -v3
	v_rndne_f32_e32 v5, v3
	v_fmac_f32_e32 v4, 0x32a5705f, v2
	v_sub_f32_e32 v3, v3, v5
	v_add_f32_e32 v3, v3, v4
	v_cvt_i32_f32_e32 v5, v5
	v_exp_f32_e32 v3, v3
	v_cmp_ngt_f32_e32 vcc, s89, v2
	v_ldexp_f32 v3, v3, v5
	s_nop 0
	v_cndmask_b32_e32 v3, 0, v3, vcc
	v_cmp_nlt_f32_e32 vcc, s90, v2
	s_nop 1
	v_cndmask_b32_e32 v2, v214, v3, vcc
	v_mul_f32_e64 v1, v1, -v2
	ds_write_b32 v0, v1 offset:768
	v_lshl_add_u32 v0, v103, 2, v130
	s_waitcnt lgkmcnt(0)
	ds_read_b32 v1, v0 offset:1280
	v_and_b32_e32 v2, 64, v215
	v_add_u32_e32 v3, -1, v215
	v_cmp_lt_i32_e32 vcc, v3, v2
	v_add_u32_e32 v4, -2, v215
	s_nop 0
	v_cndmask_b32_e32 v3, v3, v215, vcc
	v_lshlrev_b32_e32 v3, 2, v3
	s_waitcnt lgkmcnt(0)
	ds_bpermute_b32 v3, v3, v1
	v_cmp_lt_i32_e32 vcc, v4, v2
	s_waitcnt lgkmcnt(0)
	v_add_f32_e32 v3, v1, v3
	v_cndmask_b32_e32 v4, v4, v215, vcc
	v_cndmask_b32_e64 v1, v3, v1, s[16:17]
	v_lshlrev_b32_e32 v3, 2, v4
	ds_bpermute_b32 v3, v3, v1
	v_add_u32_e32 v4, -4, v215
	v_cmp_lt_i32_e32 vcc, v4, v2
	s_waitcnt lgkmcnt(0)
	v_add_f32_e32 v3, v1, v3
	v_cndmask_b32_e32 v4, v4, v215, vcc
	v_cndmask_b32_e64 v1, v3, v1, s[18:19]
	v_lshlrev_b32_e32 v3, 2, v4
	ds_bpermute_b32 v3, v3, v1
	v_add_u32_e32 v4, -8, v215
	v_cmp_lt_i32_e32 vcc, v4, v2
	s_waitcnt lgkmcnt(0)
	v_add_f32_e32 v3, v1, v3
	v_cndmask_b32_e32 v4, v4, v215, vcc
	v_cndmask_b32_e64 v1, v3, v1, s[20:21]
	v_lshlrev_b32_e32 v3, 2, v4
	ds_bpermute_b32 v3, v3, v1
	v_add_u32_e32 v4, -16, v215
	v_cmp_lt_i32_e32 vcc, v4, v2
	s_waitcnt lgkmcnt(0)
	v_add_f32_e32 v3, v1, v3
	v_cndmask_b32_e32 v4, v4, v215, vcc
	v_cndmask_b32_e64 v1, v3, v1, s[22:23]
	v_lshlrev_b32_e32 v3, 2, v4
	ds_bpermute_b32 v3, v3, v1
	v_subrev_u32_e32 v4, 32, v215
	v_cmp_lt_i32_e32 vcc, v4, v2
	s_waitcnt lgkmcnt(0)
	v_add_f32_e32 v3, v1, v3
	v_cndmask_b32_e32 v2, v4, v215, vcc
	v_cndmask_b32_e64 v1, v3, v1, s[24:25]
	v_lshlrev_b32_e32 v2, 2, v2
	ds_bpermute_b32 v2, v2, v1
	s_waitcnt lgkmcnt(0)
	v_add_f32_e32 v2, v1, v2
	v_cndmask_b32_e64 v1, v2, v1, s[26:27]
	v_mul_f32_e32 v2, 0x3fb8aa3b, v1
	v_fma_f32 v3, v1, s88, -v2
	v_rndne_f32_e32 v4, v2
	v_fmac_f32_e32 v3, 0x32a5705f, v1
	v_sub_f32_e32 v2, v2, v4
	v_add_f32_e32 v2, v2, v3
	v_cvt_i32_f32_e32 v4, v4
	v_exp_f32_e32 v2, v2
	v_cmp_ngt_f32_e32 vcc, s89, v1
	v_ldexp_f32 v2, v2, v4
	s_nop 0
	v_cndmask_b32_e32 v2, 0, v2, vcc
	v_cmp_nlt_f32_e32 vcc, s90, v1
	s_nop 1
	v_cndmask_b32_e32 v2, v214, v2, vcc
	ds_write2st64_b32 v0, v1, v2 offset0:3 offset1:4

; __device__ __forceinline__ void gdn_local_unit(LAS unsigned char* lds, const GdnP& P, int unit, const int tid, const int pf) {
;     ...
;     if (tid < 64) { float v = gb[tid];
; #pragma unroll
;         for (int o = 1; o < 64; o <<= 1) { const float y = __shfl_up(v, o); if (lane >= o) v += y; }
;         Gc[tid] = v; eG[tid] = expf(v); }
.LBB0_902:
	s_or_b64 exec, exec, s[0:1]
	s_waitcnt lgkmcnt(0)
	s_barrier
	s_and_saveexec_b64 s[0:1], s[12:13]
	s_branch .LBB0_904

; __global__ void __launch_bounds__(NTHREADS, 2) mega(Args a) {
;     ...
;         if (!(a.probe & 4)) for (int pc = gw; pc < 2048; pc += NGW) { const int part = pc & 3, it = pc >> 2, j = it & 15, bh = it >> 4, b = bh >> 3, h = bh & 7;
;             const bf16_t* kp = proj + (size_t)(b * SEQ + j * 256 + part * 64) * NIN + 1024 + h * 128 + lane * 2; float s0 = 0.f, s1 = 0.f;
; #pragma unroll 16
;             for (int r = 0; r < 64; ++r) { const unsigned v = *(const unsigned*)(kp + (size_t)r * NIN); s0 += bflo(v); s1 += bfhi(v); }
.LBB0_1046:
	s_and_b32 s1, s2, 0xfffff000
	s_and_b32 s6, s5, 0xfc0
	s_or_b32 s1, s1, s6
	s_lshl_b32 s6, s9, 1
	s_mul_hi_i32 s7, s1, 0x5a00
	s_mulk_i32 s1, 0x5a00
	s_and_b32 s6, s6, 0x700
	s_or_b32 s6, s1, s6
	v_lshl_add_u64 v[6:7], v[4:5], 0, s[6:7]
	s_mov_b64 s[6:7], 0
	v_mov_b32_e32 v8, 0
	v_mov_b32_e32 v9, v1
	s_mov_b64 s[36:37], 0x9300800
	v_lshl_add_u64 v[192:193], v[6:7], 0, s[36:37]
	s_mov_b64 s[36:37], 0x5a00
	global_load_dword v128, v[192:193], off
	v_lshl_add_u64 v[192:193], v[192:193], 0, s[36:37]
	global_load_dword v129, v[192:193], off
	v_lshl_add_u64 v[192:193], v[192:193], 0, s[36:37]
	global_load_dword v130, v[192:193], off
	v_lshl_add_u64 v[192:193], v[192:193], 0, s[36:37]
	global_load_dword v131, v[192:193], off
	v_lshl_add_u64 v[192:193], v[192:193], 0, s[36:37]
	global_load_dword v132, v[192:193], off
	v_lshl_add_u64 v[192:193], v[192:193], 0, s[36:37]
	global_load_dword v133, v[192:193], off
	v_lshl_add_u64 v[192:193], v[192:193], 0, s[36:37]
	global_load_dword v134, v[192:193], off
	v_lshl_add_u64 v[192:193], v[192:193], 0, s[36:37]
	global_load_dword v135, v[192:193], off
	v_lshl_add_u64 v[192:193], v[192:193], 0, s[36:37]
	global_load_dword v136, v[192:193], off
	v_lshl_add_u64 v[192:193], v[192:193], 0, s[36:37]
	global_load_dword v137, v[192:193], off
	v_lshl_add_u64 v[192:193], v[192:193], 0, s[36:37]
	global_load_dword v138, v[192:193], off
	v_lshl_add_u64 v[192:193], v[192:193], 0, s[36:37]
	global_load_dword v139, v[192:193], off
	v_lshl_add_u64 v[192:193], v[192:193], 0, s[36:37]
	global_load_dword v140, v[192:193], off
	v_lshl_add_u64 v[192:193], v[192:193], 0, s[36:37]
	global_load_dword v141, v[192:193], off
	v_lshl_add_u64 v[192:193], v[192:193], 0, s[36:37]
	global_load_dword v142, v[192:193], off
	v_lshl_add_u64 v[192:193], v[192:193], 0, s[36:37]
	global_load_dword v143, v[192:193], off
	v_lshl_add_u64 v[192:193], v[192:193], 0, s[36:37]
	global_load_dword v144, v[192:193], off
	v_lshl_add_u64 v[192:193], v[192:193], 0, s[36:37]
	global_load_dword v145, v[192:193], off
	v_lshl_add_u64 v[192:193], v[192:193], 0, s[36:37]
	global_load_dword v146, v[192:193], off
	v_lshl_add_u64 v[192:193], v[192:193], 0, s[36:37]
	global_load_dword v147, v[192:193], off
	v_lshl_add_u64 v[192:193], v[192:193], 0, s[36:37]
	global_load_dword v148, v[192:193], off
	v_lshl_add_u64 v[192:193], v[192:193], 0, s[36:37]
	global_load_dword v149, v[192:193], off
	v_lshl_add_u64 v[192:193], v[192:193], 0, s[36:37]
	global_load_dword v150, v[192:193], off
	v_lshl_add_u64 v[192:193], v[192:193], 0, s[36:37]
	global_load_dword v151, v[192:193], off
	v_lshl_add_u64 v[192:193], v[192:193], 0, s[36:37]
	global_load_dword v152, v[192:193], off
	v_lshl_add_u64 v[192:193], v[192:193], 0, s[36:37]
	global_load_dword v153, v[192:193], off
	v_lshl_add_u64 v[192:193], v[192:193], 0, s[36:37]
	global_load_dword v154, v[192:193], off
	v_lshl_add_u64 v[192:193], v[192:193], 0, s[36:37]
	global_load_dword v155, v[192:193], off
	v_lshl_add_u64 v[192:193], v[192:193], 0, s[36:37]
	global_load_dword v156, v[192:193], off
	v_lshl_add_u64 v[192:193], v[192:193], 0, s[36:37]
	global_load_dword v157, v[192:193], off
	v_lshl_add_u64 v[192:193], v[192:193], 0, s[36:37]
	global_load_dword v158, v[192:193], off
	v_lshl_add_u64 v[192:193], v[192:193], 0, s[36:37]
	global_load_dword v159, v[192:193], off
	v_lshl_add_u64 v[192:193], v[192:193], 0, s[36:37]
	global_load_dword v160, v[192:193], off
	v_lshl_add_u64 v[192:193], v[192:193], 0, s[36:37]
	global_load_dword v161, v[192:193], off
	v_lshl_add_u64 v[192:193], v[192:193], 0, s[36:37]
	global_load_dword v162, v[192:193], off
	v_lshl_add_u64 v[192:193], v[192:193], 0, s[36:37]
	global_load_dword v163, v[192:193], off
	v_lshl_add_u64 v[192:193], v[192:193], 0, s[36:37]
	global_load_dword v164, v[192:193], off
	v_lshl_add_u64 v[192:193], v[192:193], 0, s[36:37]
	global_load_dword v165, v[192:193], off
	v_lshl_add_u64 v[192:193], v[192:193], 0, s[36:37]
	global_load_dword v166, v[192:193], off
	v_lshl_add_u64 v[192:193], v[192:193], 0, s[36:37]
	global_load_dword v167, v[192:193], off
	v_lshl_add_u64 v[192:193], v[192:193], 0, s[36:37]
	global_load_dword v168, v[192:193], off
	v_lshl_add_u64 v[192:193], v[192:193], 0, s[36:37]
	global_load_dword v169, v[192:193], off
	v_lshl_add_u64 v[192:193], v[192:193], 0, s[36:37]
	global_load_dword v170, v[192:193], off
	v_lshl_add_u64 v[192:193], v[192:193], 0, s[36:37]
	global_load_dword v171, v[192:193], off
	v_lshl_add_u64 v[192:193], v[192:193], 0, s[36:37]
	global_load_dword v172, v[192:193], off
	v_lshl_add_u64 v[192:193], v[192:193], 0, s[36:37]
	global_load_dword v173, v[192:193], off
	v_lshl_add_u64 v[192:193], v[192:193], 0, s[36:37]
	global_load_dword v174, v[192:193], off
	v_lshl_add_u64 v[192:193], v[192:193], 0, s[36:37]
	global_load_dword v175, v[192:193], off
	v_lshl_add_u64 v[192:193], v[192:193], 0, s[36:37]
	global_load_dword v176, v[192:193], off
	v_lshl_add_u64 v[192:193], v[192:193], 0, s[36:37]
	global_load_dword v177, v[192:193], off
	v_lshl_add_u64 v[192:193], v[192:193], 0, s[36:37]
	global_load_dword v178, v[192:193], off
	v_lshl_add_u64 v[192:193], v[192:193], 0, s[36:37]
	global_load_dword v179, v[192:193], off
	v_lshl_add_u64 v[192:193], v[192:193], 0, s[36:37]
	global_load_dword v180, v[192:193], off
	v_lshl_add_u64 v[192:193], v[192:193], 0, s[36:37]
	global_load_dword v181, v[192:193], off
	v_lshl_add_u64 v[192:193], v[192:193], 0, s[36:37]
	global_load_dword v182, v[192:193], off
	v_lshl_add_u64 v[192:193], v[192:193], 0, s[36:37]
	global_load_dword v183, v[192:193], off
	v_lshl_add_u64 v[192:193], v[192:193], 0, s[36:37]
	global_load_dword v184, v[192:193], off
	v_lshl_add_u64 v[192:193], v[192:193], 0, s[36:37]
	global_load_dword v185, v[192:193], off
	v_lshl_add_u64 v[192:193], v[192:193], 0, s[36:37]
	global_load_dword v186, v[192:193], off
	v_lshl_add_u64 v[192:193], v[192:193], 0, s[36:37]
	global_load_dword v187, v[192:193], off
	v_lshl_add_u64 v[192:193], v[192:193], 0, s[36:37]
	global_load_dword v188, v[192:193], off
	v_lshl_add_u64 v[192:193], v[192:193], 0, s[36:37]
	global_load_dword v189, v[192:193], off
	v_lshl_add_u64 v[192:193], v[192:193], 0, s[36:37]
	global_load_dword v190, v[192:193], off
	v_lshl_add_u64 v[192:193], v[192:193], 0, s[36:37]
	global_load_dword v191, v[192:193], off
	s_waitcnt vmcnt(63)
; __global__ void __launch_bounds__(NTHREADS, 2) mega(Args a) {
;     ...
;             for (int r = 0; r < 64; ++r) { const unsigned v = *(const unsigned*)(kp + (size_t)r * NIN); s0 += bflo(v); s1 += bfhi(v); }
	v_lshlrev_b32_e32 v10, 16, v128
	v_and_b32_e32 v11, 0xffff0000, v128
	v_pk_add_f32 v[8:9], v[8:9], v[10:11]
	s_waitcnt vmcnt(62)
	v_lshlrev_b32_e32 v10, 16, v129
	v_and_b32_e32 v11, 0xffff0000, v129
	v_pk_add_f32 v[8:9], v[8:9], v[10:11]
	s_waitcnt vmcnt(61)
	v_lshlrev_b32_e32 v10, 16, v130
	v_and_b32_e32 v11, 0xffff0000, v130
	v_pk_add_f32 v[8:9], v[8:9], v[10:11]
	s_waitcnt vmcnt(60)
	v_lshlrev_b32_e32 v10, 16, v131
	v_and_b32_e32 v11, 0xffff0000, v131
	v_pk_add_f32 v[8:9], v[8:9], v[10:11]
	s_waitcnt vmcnt(59)
	v_lshlrev_b32_e32 v10, 16, v132
	v_and_b32_e32 v11, 0xffff0000, v132
	v_pk_add_f32 v[8:9], v[8:9], v[10:11]
	s_waitcnt vmcnt(58)
	v_lshlrev_b32_e32 v10, 16, v133
	v_and_b32_e32 v11, 0xffff0000, v133
	v_pk_add_f32 v[8:9], v[8:9], v[10:11]
	s_waitcnt vmcnt(57)
	v_lshlrev_b32_e32 v10, 16, v134
	v_and_b32_e32 v11, 0xffff0000, v134
	v_pk_add_f32 v[8:9], v[8:9], v[10:11]
	s_waitcnt vmcnt(56)
	v_lshlrev_b32_e32 v10, 16, v135
	v_and_b32_e32 v11, 0xffff0000, v135
	v_pk_add_f32 v[8:9], v[8:9], v[10:11]
	s_waitcnt vmcnt(55)
	v_lshlrev_b32_e32 v10, 16, v136
	v_and_b32_e32 v11, 0xffff0000, v136
	v_pk_add_f32 v[8:9], v[8:9], v[10:11]
	s_waitcnt vmcnt(54)
	v_lshlrev_b32_e32 v10, 16, v137
	v_and_b32_e32 v11, 0xffff0000, v137
	v_pk_add_f32 v[8:9], v[8:9], v[10:11]
	s_waitcnt vmcnt(53)
	v_lshlrev_b32_e32 v10, 16, v138
	v_and_b32_e32 v11, 0xffff0000, v138
	v_pk_add_f32 v[8:9], v[8:9], v[10:11]
	s_waitcnt vmcnt(52)
	v_lshlrev_b32_e32 v10, 16, v139
	v_and_b32_e32 v11, 0xffff0000, v139
	v_pk_add_f32 v[8:9], v[8:9], v[10:11]
	s_waitcnt vmcnt(51)
	v_lshlrev_b32_e32 v10, 16, v140
	v_and_b32_e32 v11, 0xffff0000, v140
	v_pk_add_f32 v[8:9], v[8:9], v[10:11]
	s_waitcnt vmcnt(50)
	v_lshlrev_b32_e32 v10, 16, v141
	v_and_b32_e32 v11, 0xffff0000, v141
	v_pk_add_f32 v[8:9], v[8:9], v[10:11]
	s_waitcnt vmcnt(49)
	v_lshlrev_b32_e32 v10, 16, v142
	v_and_b32_e32 v11, 0xffff0000, v142
	v_pk_add_f32 v[8:9], v[8:9], v[10:11]
	s_waitcnt vmcnt(48)
	v_lshlrev_b32_e32 v10, 16, v143
	v_and_b32_e32 v11, 0xffff0000, v143
	v_pk_add_f32 v[8:9], v[8:9], v[10:11]
	s_waitcnt vmcnt(47)
	v_lshlrev_b32_e32 v10, 16, v144
	v_and_b32_e32 v11, 0xffff0000, v144
	v_pk_add_f32 v[8:9], v[8:9], v[10:11]
	s_waitcnt vmcnt(46)
	v_lshlrev_b32_e32 v10, 16, v145
	v_and_b32_e32 v11, 0xffff0000, v145
	v_pk_add_f32 v[8:9], v[8:9], v[10:11]
	s_waitcnt vmcnt(45)
	v_lshlrev_b32_e32 v10, 16, v146
	v_and_b32_e32 v11, 0xffff0000, v146
	v_pk_add_f32 v[8:9], v[8:9], v[10:11]
	s_waitcnt vmcnt(44)
	v_lshlrev_b32_e32 v10, 16, v147
	v_and_b32_e32 v11, 0xffff0000, v147
	v_pk_add_f32 v[8:9], v[8:9], v[10:11]
	s_waitcnt vmcnt(43)
	v_lshlrev_b32_e32 v10, 16, v148
	v_and_b32_e32 v11, 0xffff0000, v148
	v_pk_add_f32 v[8:9], v[8:9], v[10:11]
	s_waitcnt vmcnt(42)
	v_lshlrev_b32_e32 v10, 16, v149
	v_and_b32_e32 v11, 0xffff0000, v149
	v_pk_add_f32 v[8:9], v[8:9], v[10:11]
	s_waitcnt vmcnt(41)
	v_lshlrev_b32_e32 v10, 16, v150
	v_and_b32_e32 v11, 0xffff0000, v150
	v_pk_add_f32 v[8:9], v[8:9], v[10:11]
	s_waitcnt vmcnt(40)
	v_lshlrev_b32_e32 v10, 16, v151
	v_and_b32_e32 v11, 0xffff0000, v151
	v_pk_add_f32 v[8:9], v[8:9], v[10:11]
	s_waitcnt vmcnt(39)
	v_lshlrev_b32_e32 v10, 16, v152
	v_and_b32_e32 v11, 0xffff0000, v152
	v_pk_add_f32 v[8:9], v[8:9], v[10:11]
	s_waitcnt vmcnt(38)
	v_lshlrev_b32_e32 v10, 16, v153
	v_and_b32_e32 v11, 0xffff0000, v153
	v_pk_add_f32 v[8:9], v[8:9], v[10:11]
	s_waitcnt vmcnt(37)
	v_lshlrev_b32_e32 v10, 16, v154
	v_and_b32_e32 v11, 0xffff0000, v154
	v_pk_add_f32 v[8:9], v[8:9], v[10:11]
	s_waitcnt vmcnt(36)
	v_lshlrev_b32_e32 v10, 16, v155
	v_and_b32_e32 v11, 0xffff0000, v155
	v_pk_add_f32 v[8:9], v[8:9], v[10:11]
	s_waitcnt vmcnt(35)
	v_lshlrev_b32_e32 v10, 16, v156
	v_and_b32_e32 v11, 0xffff0000, v156
	v_pk_add_f32 v[8:9], v[8:9], v[10:11]
	s_waitcnt vmcnt(34)
	v_lshlrev_b32_e32 v10, 16, v157
	v_and_b32_e32 v11, 0xffff0000, v157
	v_pk_add_f32 v[8:9], v[8:9], v[10:11]
	s_waitcnt vmcnt(33)
	v_lshlrev_b32_e32 v10, 16, v158
	v_and_b32_e32 v11, 0xffff0000, v158
	v_pk_add_f32 v[8:9], v[8:9], v[10:11]
	s_waitcnt vmcnt(32)
	v_lshlrev_b32_e32 v10, 16, v159
	v_and_b32_e32 v11, 0xffff0000, v159
	v_pk_add_f32 v[8:9], v[8:9], v[10:11]
	s_waitcnt vmcnt(31)
	v_lshlrev_b32_e32 v10, 16, v160
	v_and_b32_e32 v11, 0xffff0000, v160
	v_pk_add_f32 v[8:9], v[8:9], v[10:11]
	s_waitcnt vmcnt(30)
; __global__ void __launch_bounds__(NTHREADS, 2) mega(Args a) {
;     ...
;             const bf16_t* kp = proj + (size_t)(b * SEQ + j * 256 + part * 64) * NIN + 1024 + h * 128 + lane * 2; float s0 = 0.f, s1 = 0.f;
; #pragma unroll 16
;             for (int r = 0; r < 64; ++r) { const unsigned v = *(const unsigned*)(kp + (size_t)r * NIN); s0 += bflo(v); s1 += bfhi(v); }
;             kmean[(size_t)pc * 128 + lane * 2] = s0 * (1.f / 256.f); kmean[(size_t)pc * 128 + lane * 2 + 1] = s1 * (1.f / 256.f); }
	v_lshlrev_b32_e32 v10, 16, v161
	v_and_b32_e32 v11, 0xffff0000, v161
	v_pk_add_f32 v[8:9], v[8:9], v[10:11]
	s_waitcnt vmcnt(29)
	v_lshlrev_b32_e32 v10, 16, v162
	v_and_b32_e32 v11, 0xffff0000, v162
	v_pk_add_f32 v[8:9], v[8:9], v[10:11]
	s_waitcnt vmcnt(28)
	v_lshlrev_b32_e32 v10, 16, v163
	v_and_b32_e32 v11, 0xffff0000, v163
	v_pk_add_f32 v[8:9], v[8:9], v[10:11]
	s_waitcnt vmcnt(27)
	v_lshlrev_b32_e32 v10, 16, v164
	v_and_b32_e32 v11, 0xffff0000, v164
	v_pk_add_f32 v[8:9], v[8:9], v[10:11]
	s_waitcnt vmcnt(26)
	v_lshlrev_b32_e32 v10, 16, v165
	v_and_b32_e32 v11, 0xffff0000, v165
	v_pk_add_f32 v[8:9], v[8:9], v[10:11]
	s_waitcnt vmcnt(25)
	v_lshlrev_b32_e32 v10, 16, v166
	v_and_b32_e32 v11, 0xffff0000, v166
	v_pk_add_f32 v[8:9], v[8:9], v[10:11]
	s_waitcnt vmcnt(24)
	v_lshlrev_b32_e32 v10, 16, v167
	v_and_b32_e32 v11, 0xffff0000, v167
	v_pk_add_f32 v[8:9], v[8:9], v[10:11]
	s_waitcnt vmcnt(23)
	v_lshlrev_b32_e32 v10, 16, v168
	v_and_b32_e32 v11, 0xffff0000, v168
	v_pk_add_f32 v[8:9], v[8:9], v[10:11]
	s_waitcnt vmcnt(22)
	v_lshlrev_b32_e32 v10, 16, v169
	v_and_b32_e32 v11, 0xffff0000, v169
	v_pk_add_f32 v[8:9], v[8:9], v[10:11]
	s_waitcnt vmcnt(21)
	v_lshlrev_b32_e32 v10, 16, v170
	v_and_b32_e32 v11, 0xffff0000, v170
	v_pk_add_f32 v[8:9], v[8:9], v[10:11]
	s_waitcnt vmcnt(20)
	v_lshlrev_b32_e32 v10, 16, v171
	v_and_b32_e32 v11, 0xffff0000, v171
	v_pk_add_f32 v[8:9], v[8:9], v[10:11]
	s_waitcnt vmcnt(19)
	v_lshlrev_b32_e32 v10, 16, v172
	v_and_b32_e32 v11, 0xffff0000, v172
	v_pk_add_f32 v[8:9], v[8:9], v[10:11]
	s_waitcnt vmcnt(18)
	v_lshlrev_b32_e32 v10, 16, v173
	v_and_b32_e32 v11, 0xffff0000, v173
	v_pk_add_f32 v[8:9], v[8:9], v[10:11]
	s_waitcnt vmcnt(17)
	v_lshlrev_b32_e32 v10, 16, v174
	v_and_b32_e32 v11, 0xffff0000, v174
	v_pk_add_f32 v[8:9], v[8:9], v[10:11]
	s_waitcnt vmcnt(16)
	v_lshlrev_b32_e32 v10, 16, v175
	v_and_b32_e32 v11, 0xffff0000, v175
	v_pk_add_f32 v[8:9], v[8:9], v[10:11]
	s_waitcnt vmcnt(15)
	v_lshlrev_b32_e32 v10, 16, v176
	v_and_b32_e32 v11, 0xffff0000, v176
	v_pk_add_f32 v[8:9], v[8:9], v[10:11]
	s_waitcnt vmcnt(14)
	v_lshlrev_b32_e32 v10, 16, v177
	v_and_b32_e32 v11, 0xffff0000, v177
	v_pk_add_f32 v[8:9], v[8:9], v[10:11]
	s_waitcnt vmcnt(13)
	v_lshlrev_b32_e32 v10, 16, v178
	v_and_b32_e32 v11, 0xffff0000, v178
	v_pk_add_f32 v[8:9], v[8:9], v[10:11]
	s_waitcnt vmcnt(12)
	v_lshlrev_b32_e32 v10, 16, v179
	v_and_b32_e32 v11, 0xffff0000, v179
	v_pk_add_f32 v[8:9], v[8:9], v[10:11]
	s_waitcnt vmcnt(11)
	v_lshlrev_b32_e32 v10, 16, v180
	v_and_b32_e32 v11, 0xffff0000, v180
	v_pk_add_f32 v[8:9], v[8:9], v[10:11]
	s_waitcnt vmcnt(10)
	v_lshlrev_b32_e32 v10, 16, v181
	v_and_b32_e32 v11, 0xffff0000, v181
	v_pk_add_f32 v[8:9], v[8:9], v[10:11]
	s_waitcnt vmcnt(9)
	v_lshlrev_b32_e32 v10, 16, v182
	v_and_b32_e32 v11, 0xffff0000, v182
	v_pk_add_f32 v[8:9], v[8:9], v[10:11]
	s_waitcnt vmcnt(8)
	v_lshlrev_b32_e32 v10, 16, v183
	v_and_b32_e32 v11, 0xffff0000, v183
	v_pk_add_f32 v[8:9], v[8:9], v[10:11]
	s_waitcnt vmcnt(7)
	v_lshlrev_b32_e32 v10, 16, v184
	v_and_b32_e32 v11, 0xffff0000, v184
	v_pk_add_f32 v[8:9], v[8:9], v[10:11]
	s_waitcnt vmcnt(6)
	v_lshlrev_b32_e32 v10, 16, v185
	v_and_b32_e32 v11, 0xffff0000, v185
	v_pk_add_f32 v[8:9], v[8:9], v[10:11]
	s_waitcnt vmcnt(5)
	v_lshlrev_b32_e32 v10, 16, v186
	v_and_b32_e32 v11, 0xffff0000, v186
	v_pk_add_f32 v[8:9], v[8:9], v[10:11]
	s_waitcnt vmcnt(4)
	v_lshlrev_b32_e32 v10, 16, v187
	v_and_b32_e32 v11, 0xffff0000, v187
	v_pk_add_f32 v[8:9], v[8:9], v[10:11]
	s_waitcnt vmcnt(3)
	v_lshlrev_b32_e32 v10, 16, v188
	v_and_b32_e32 v11, 0xffff0000, v188
	v_pk_add_f32 v[8:9], v[8:9], v[10:11]
	s_waitcnt vmcnt(2)
	v_lshlrev_b32_e32 v10, 16, v189
	v_and_b32_e32 v11, 0xffff0000, v189
	v_pk_add_f32 v[8:9], v[8:9], v[10:11]
	s_waitcnt vmcnt(1)
	v_lshlrev_b32_e32 v10, 16, v190
	v_and_b32_e32 v11, 0xffff0000, v190
	v_pk_add_f32 v[8:9], v[8:9], v[10:11]
	s_waitcnt vmcnt(0)
	v_lshlrev_b32_e32 v10, 16, v191
	v_and_b32_e32 v11, 0xffff0000, v191
	v_pk_add_f32 v[8:9], v[8:9], v[10:11]
	s_ashr_i32 s1, s0, 31
	v_pk_mul_f32 v[6:7], v[8:9], s[4:5] op_sel_hi:[1,0]
	s_lshl_b64 s[6:7], s[0:1], 9
	s_add_i32 s0, s0, s62
	s_add_i32 s2, s2, s3
	s_add_i32 s5, s5, s8
	s_add_i32 s9, s9, s10
	v_lshl_add_u64 v[8:9], v[2:3], 0, s[6:7]
	s_cmpk_gt_i32 s0, 0x7ff
	global_store_dwordx2 v[8:9], v[6:7], off
	s_cbranch_scc0 .LBB0_1046
